# nt policy also on the sample memory-attention V row stream (contiguous, read once); K stream left default
# speedup vs baseline: 1.0040x; 1.0008x over previous
; __device__ __forceinline__ void memattn_unit(const Ctx& C, int r0, const float* kp0, const float* vp0, unsigned char* lds, int lane) {
;     ...
;     __syncthreads();
; #pragma unroll
;     for (int rr = 0; rr < 4; ++rr) {
;         float* row = logits + (4 * w + rr) * 256; float x[4]; float mx = -INFINITY;
; #pragma unroll
;         for (int j = 0; j < 4; ++j) { x[j] = row[lane + 64 * j]; mx = fmaxf(mx, x[j]); }
;         mx = wave_max(mx); float s = 0.f;
; #pragma unroll
;         for (int j = 0; j < 4; ++j) { x[j] = __builtin_amdgcn_exp2f(x[j] - mx); s += x[j]; }
;         s = wave_sum(s); const float is = 1.0f / s;
; #pragma unroll
;         for (int j = 0; j < 4; ++j) row[lane + 64 * j] = x[j] * is;
;     }
;     __syncthreads();
;     {
;         const int hw = w >> 1;
;         float acc[8][2];
; #pragma unroll
;         for (int qi = 0; qi < 8; ++qi) { acc[qi][0] = 0.f; acc[qi][1] = 0.f; }
;         const float* vbase = vp0 + 128 * w + 2 * lane;
;         float2 va[16];
; #pragma unroll
;         for (int u = 0; u < 16; ++u) va[u] = *(const float2*)(vbase + (size_t)u * 1024);
.LBB0_3210:
	v_and_b32_e32 v0, 64, v116
	v_add_u32_e32 v8, 64, v0
	v_xor_b32_e32 v0, 1, v116
	v_cmp_lt_i32_e32 vcc, v0, v8
	v_lshl_add_u32 v9, v117, 2, s33
	s_waitcnt lgkmcnt(0)
	s_barrier
	v_cndmask_b32_e32 v4, v116, v0, vcc
	ds_read2st64_b32 v[0:1], v9 offset1:1
	ds_read2st64_b32 v[2:3], v9 offset0:2 offset1:3
	v_lshlrev_b32_e32 v10, 2, v4
	v_xor_b32_e32 v13, 2, v116
	v_cmp_lt_i32_e32 vcc, v13, v8
	s_waitcnt lgkmcnt(1)
	v_max3_f32 v11, v0, s53, v1
	s_waitcnt lgkmcnt(0)
	v_max3_f32 v11, v11, v2, v3
	ds_bpermute_b32 v12, v10, v11
	v_cndmask_b32_e32 v13, v116, v13, vcc
	v_lshlrev_b32_e32 v13, 2, v13
	v_xor_b32_e32 v14, 4, v116
	v_cmp_lt_i32_e32 vcc, v14, v8
	s_waitcnt lgkmcnt(0)
	v_max_f32_e32 v12, v12, v12
	v_max_f32_e32 v11, v11, v12
	ds_bpermute_b32 v12, v13, v11
	v_cndmask_b32_e32 v14, v116, v14, vcc
	v_lshlrev_b32_e32 v14, 2, v14
	v_xor_b32_e32 v15, 8, v116
	v_cmp_lt_i32_e32 vcc, v15, v8
	s_waitcnt lgkmcnt(0)
	v_max_f32_e32 v12, v12, v12
	v_max_f32_e32 v11, v11, v12
	ds_bpermute_b32 v12, v14, v11
	v_cndmask_b32_e32 v15, v116, v15, vcc
	v_lshlrev_b32_e32 v15, 2, v15
	v_xor_b32_e32 v16, 16, v116
	v_cmp_lt_i32_e32 vcc, v16, v8
	s_waitcnt lgkmcnt(0)
	v_max_f32_e32 v12, v12, v12
	v_max_f32_e32 v11, v11, v12
	ds_bpermute_b32 v12, v15, v11
	v_cndmask_b32_e32 v16, v116, v16, vcc
	v_lshlrev_b32_e32 v16, 2, v16
	v_xor_b32_e32 v17, 32, v116
	v_cmp_lt_i32_e32 vcc, v17, v8
	s_waitcnt lgkmcnt(0)
	v_max_f32_e32 v12, v12, v12
	v_max_f32_e32 v11, v11, v12
	ds_bpermute_b32 v12, v16, v11
	v_cndmask_b32_e32 v8, v116, v17, vcc
	v_lshlrev_b32_e32 v8, 2, v8
	ds_read2st64_b32 v[4:5], v9 offset0:4 offset1:5
	ds_read2st64_b32 v[6:7], v9 offset0:6 offset1:7
	s_ashr_i32 s35, s34, 31
	s_waitcnt lgkmcnt(2)
	v_max_f32_e32 v12, v12, v12
	v_max_f32_e32 v11, v11, v12
	ds_bpermute_b32 v12, v8, v11
	v_mov_b32_e32 v34, 0
	s_mov_b32 s4, s44
	v_mov_b32_e32 v35, v34
	v_mov_b32_e32 v58, v34
	s_waitcnt lgkmcnt(0)
	v_max_f32_e32 v12, v12, v12
	v_max_f32_e32 v11, v11, v12
	v_sub_f32_e32 v0, v0, v11
	v_exp_f32_e32 v12, v0
	v_sub_f32_e32 v0, v1, v11
	v_exp_f32_e32 v17, v0
	v_sub_f32_e32 v0, v2, v11
	v_exp_f32_e32 v18, v0
	v_sub_f32_e32 v0, v3, v11
	v_exp_f32_e32 v11, v0
	v_add_f32_e32 v0, 0, v12
	v_add_f32_e32 v0, v17, v0
	v_add_f32_e32 v0, v18, v0
	v_add_f32_e32 v0, v11, v0
	ds_bpermute_b32 v1, v10, v0
	v_max3_f32 v2, v4, s53, v5
	v_max3_f32 v2, v2, v6, v7
	ds_bpermute_b32 v3, v10, v2
	v_mov_b32_e32 v59, v34
	s_waitcnt lgkmcnt(1)
	v_add_f32_e32 v0, v0, v1
	ds_bpermute_b32 v1, v13, v0
	v_mov_b32_e32 v68, v34
	s_waitcnt lgkmcnt(1)
	v_max_f32_e32 v3, v3, v3
	v_max_f32_e32 v2, v2, v3
	ds_bpermute_b32 v3, v13, v2
	s_waitcnt lgkmcnt(1)
	v_add_f32_e32 v0, v0, v1
	ds_bpermute_b32 v1, v14, v0
	v_mov_b32_e32 v69, v34
	v_mov_b32_e32 v72, v34
	s_waitcnt lgkmcnt(1)
	v_max_f32_e32 v3, v3, v3
	v_max_f32_e32 v2, v2, v3
	s_waitcnt lgkmcnt(0)
	v_add_f32_e32 v0, v0, v1
	ds_bpermute_b32 v1, v15, v0
	ds_bpermute_b32 v3, v14, v2
	v_mov_b32_e32 v73, v34
	v_mov_b32_e32 v56, v34
	v_mov_b32_e32 v57, v34
	s_waitcnt lgkmcnt(1)
	v_add_f32_e32 v0, v0, v1
	s_waitcnt lgkmcnt(0)
	v_max_f32_e32 v1, v3, v3
	v_max_f32_e32 v1, v2, v1
	ds_bpermute_b32 v2, v15, v1
	ds_bpermute_b32 v3, v16, v0
	v_mov_b32_e32 v64, v34
	v_mov_b32_e32 v65, v34
	v_mov_b32_e32 v70, v34
	s_waitcnt lgkmcnt(1)
	v_max_f32_e32 v2, v2, v2
	v_max_f32_e32 v1, v1, v2
	s_waitcnt lgkmcnt(0)
	v_add_f32_e32 v0, v0, v3
	ds_bpermute_b32 v2, v16, v1
	ds_bpermute_b32 v3, v8, v0
	v_mov_b32_e32 v71, v34
	v_mov_b32_e32 v74, v34
	v_mov_b32_e32 v75, v34
	s_waitcnt lgkmcnt(1)
	v_max_f32_e32 v2, v2, v2
	s_waitcnt lgkmcnt(0)
	v_add_f32_e32 v19, v0, v3
	v_max_f32_e32 v0, v1, v2
	ds_bpermute_b32 v1, v8, v0
	v_div_scale_f32 v20, s[0:1], v19, v19, 1.0
	v_rcp_f32_e32 v21, v20
	v_div_scale_f32 v26, vcc, 1.0, v19, 1.0
	s_waitcnt lgkmcnt(0)
	v_max_f32_e32 v1, v1, v1
	v_max_f32_e32 v0, v0, v1
	v_sub_f32_e32 v1, v4, v0
	v_exp_f32_e32 v22, v1
	v_sub_f32_e32 v1, v5, v0
	v_exp_f32_e32 v23, v1
	v_sub_f32_e32 v1, v6, v0
	v_exp_f32_e32 v24, v1
	v_sub_f32_e32 v0, v7, v0
	v_exp_f32_e32 v25, v0
	v_add_f32_e32 v0, 0, v22
	v_add_f32_e32 v0, v23, v0
	v_add_f32_e32 v0, v24, v0
	v_add_f32_e32 v0, v25, v0
	ds_bpermute_b32 v1, v10, v0
	v_fma_f32 v2, -v20, v21, 1.0
	v_fmac_f32_e32 v21, v2, v21
	v_mul_f32_e32 v27, v26, v21
	v_fma_f32 v28, -v20, v27, v26
	s_waitcnt lgkmcnt(0)
	v_add_f32_e32 v29, v0, v1
	ds_read2st64_b32 v[0:1], v9 offset0:8 offset1:9
	ds_read2st64_b32 v[2:3], v9 offset0:10 offset1:11
	ds_bpermute_b32 v30, v13, v29
	v_fmac_f32_e32 v27, v28, v21
	v_fma_f32 v20, -v20, v27, v26
	s_waitcnt lgkmcnt(2)
	v_max3_f32 v31, v0, s53, v1
	s_waitcnt lgkmcnt(1)
	v_max3_f32 v31, v31, v2, v3
	ds_bpermute_b32 v32, v10, v31
	s_waitcnt lgkmcnt(1)
	v_add_f32_e32 v26, v29, v30
	ds_bpermute_b32 v28, v14, v26
	v_div_fmas_f32 v20, v20, v21, v27
	v_div_fixup_f32 v19, v20, v19, 1.0
	s_waitcnt lgkmcnt(1)
	v_max_f32_e32 v29, v32, v32
	v_max_f32_e32 v29, v31, v29
	ds_bpermute_b32 v30, v13, v29
	s_waitcnt lgkmcnt(1)
	v_add_f32_e32 v21, v26, v28
	ds_bpermute_b32 v26, v15, v21
	v_mul_f32_e32 v12, v12, v19
	v_mul_f32_e32 v17, v17, v19
	s_waitcnt lgkmcnt(1)
	v_max_f32_e32 v27, v30, v30
	v_max_f32_e32 v27, v29, v27
	ds_bpermute_b32 v28, v14, v27
	s_waitcnt lgkmcnt(1)
	v_add_f32_e32 v20, v21, v26
	ds_read2st64_b32 v[4:5], v9 offset0:12 offset1:13
	ds_read2st64_b32 v[6:7], v9 offset0:14 offset1:15
	ds_write2st64_b32 v9, v12, v17 offset1:1
	v_mul_f32_e32 v18, v18, v19
	s_waitcnt lgkmcnt(3)
	v_max_f32_e32 v26, v28, v28
	v_max_f32_e32 v26, v27, v26
	ds_bpermute_b32 v27, v15, v26
	v_mul_f32_e32 v11, v11, v19
	ds_write2st64_b32 v9, v18, v11 offset0:2 offset1:3
	s_waitcnt lgkmcnt(4)
	v_max3_f32 v18, v4, s53, v5
	s_waitcnt lgkmcnt(3)
; __device__ __forceinline__ void memattn_unit(const Ctx& C, int r0, const float* kp0, const float* vp0, unsigned char* lds, int lane) {
;     ...
;         float* row = logits + (4 * w + rr) * 256; float x[4]; float mx = -INFINITY;
; #pragma unroll
;         for (int j = 0; j < 4; ++j) { x[j] = row[lane + 64 * j]; mx = fmaxf(mx, x[j]); }
;         mx = wave_max(mx); float s = 0.f;
; #pragma unroll
;         for (int j = 0; j < 4; ++j) { x[j] = __builtin_amdgcn_exp2f(x[j] - mx); s += x[j]; }
;         s = wave_sum(s); const float is = 1.0f / s;
; #pragma unroll
;         for (int j = 0; j < 4; ++j) row[lane + 64 * j] = x[j] * is;
;     }
;     __syncthreads();
;     {
;         const int hw = w >> 1;
;         float acc[8][2];
; #pragma unroll
;         for (int qi = 0; qi < 8; ++qi) { acc[qi][0] = 0.f; acc[qi][1] = 0.f; }
;         const float* vbase = vp0 + 128 * w + 2 * lane;
;         float2 va[16];
; #pragma unroll
;         for (int u = 0; u < 16; ++u) va[u] = *(const float2*)(vbase + (size_t)u * 1024);
	v_max3_f32 v18, v18, v6, v7
	s_waitcnt lgkmcnt(1)
	v_max_f32_e32 v12, v27, v27
	v_max_f32_e32 v12, v26, v12
	ds_bpermute_b32 v17, v16, v12
	ds_bpermute_b32 v19, v10, v18
	ds_bpermute_b32 v21, v16, v20
	s_waitcnt lgkmcnt(2)
	v_max_f32_e32 v17, v17, v17
	v_max_f32_e32 v12, v12, v17
	ds_bpermute_b32 v17, v8, v12
	s_waitcnt lgkmcnt(1)
	v_add_f32_e32 v20, v20, v21
	ds_bpermute_b32 v21, v8, v20
	s_waitcnt lgkmcnt(1)
	v_max_f32_e32 v17, v17, v17
	v_max_f32_e32 v12, v12, v17
	v_sub_f32_e32 v0, v0, v12
	v_sub_f32_e32 v1, v1, v12
	v_sub_f32_e32 v2, v2, v12
	v_sub_f32_e32 v3, v3, v12
	v_max_f32_e32 v12, v19, v19
	v_max_f32_e32 v12, v18, v12
	ds_bpermute_b32 v18, v13, v12
	v_exp_f32_e32 v0, v0
	v_exp_f32_e32 v1, v1
	v_exp_f32_e32 v2, v2
	v_exp_f32_e32 v3, v3
	s_waitcnt lgkmcnt(0)
	v_max_f32_e32 v18, v18, v18
	v_max_f32_e32 v12, v12, v18
	ds_bpermute_b32 v18, v14, v12
	v_add_f32_e32 v17, 0, v0
	v_add_f32_e32 v17, v1, v17
	v_add_f32_e32 v17, v2, v17
	v_add_f32_e32 v17, v3, v17
	s_waitcnt lgkmcnt(0)
	v_max_f32_e32 v18, v18, v18
	v_max_f32_e32 v12, v12, v18
	ds_bpermute_b32 v18, v15, v12
	ds_bpermute_b32 v19, v10, v17
	v_add_f32_e32 v20, v20, v21
	v_div_scale_f32 v21, s[0:1], v20, v20, 1.0
	s_waitcnt lgkmcnt(1)
	v_max_f32_e32 v18, v18, v18
	v_max_f32_e32 v12, v12, v18
	ds_bpermute_b32 v18, v16, v12
	s_waitcnt lgkmcnt(1)
	v_add_f32_e32 v17, v17, v19
	ds_bpermute_b32 v19, v13, v17
	v_rcp_f32_e32 v26, v21
	s_waitcnt lgkmcnt(1)
	v_max_f32_e32 v18, v18, v18
	v_max_f32_e32 v12, v12, v18
	ds_bpermute_b32 v18, v8, v12
	s_waitcnt lgkmcnt(1)
	v_add_f32_e32 v17, v17, v19
	ds_bpermute_b32 v19, v14, v17
	v_fma_f32 v11, -v21, v26, 1.0
	v_fmac_f32_e32 v26, v11, v26
	s_waitcnt lgkmcnt(1)
	v_max_f32_e32 v18, v18, v18
	v_max_f32_e32 v12, v12, v18
	v_sub_f32_e32 v4, v4, v12
	v_exp_f32_e32 v4, v4
	v_sub_f32_e32 v5, v5, v12
	s_waitcnt lgkmcnt(0)
	v_add_f32_e32 v17, v17, v19
	v_exp_f32_e32 v5, v5
	v_sub_f32_e32 v6, v6, v12
	ds_bpermute_b32 v19, v15, v17
	v_exp_f32_e32 v6, v6
	v_sub_f32_e32 v7, v7, v12
	v_exp_f32_e32 v7, v7
	v_add_f32_e32 v12, 0, v4
	v_add_f32_e32 v12, v5, v12
	v_add_f32_e32 v12, v6, v12
	s_waitcnt lgkmcnt(0)
	v_add_f32_e32 v17, v17, v19
	v_add_f32_e32 v12, v7, v12
	ds_bpermute_b32 v19, v16, v17
	ds_bpermute_b32 v10, v10, v12
	v_div_scale_f32 v11, vcc, 1.0, v20, 1.0
	v_mul_f32_e32 v27, v11, v26
	s_waitcnt lgkmcnt(1)
	v_add_f32_e32 v17, v17, v19
	s_waitcnt lgkmcnt(0)
	v_add_f32_e32 v10, v12, v10
	ds_bpermute_b32 v18, v8, v17
	ds_bpermute_b32 v12, v13, v10
	v_fma_f32 v28, -v21, v27, v11
	v_fmac_f32_e32 v27, v28, v26
	v_fma_f32 v11, -v21, v27, v11
	s_waitcnt lgkmcnt(1)
	v_add_f32_e32 v13, v17, v18
	s_waitcnt lgkmcnt(0)
	v_add_f32_e32 v10, v10, v12
	v_div_scale_f32 v17, s[0:1], v13, v13, 1.0
	ds_bpermute_b32 v12, v14, v10
	v_rcp_f32_e32 v18, v17
	v_div_fmas_f32 v11, v11, v26, v27
	v_div_fixup_f32 v11, v11, v20, 1.0
	v_mul_f32_e32 v20, v22, v11
	v_mul_f32_e32 v21, v23, v11
	v_mul_f32_e32 v19, v24, v11
	v_mul_f32_e32 v11, v25, v11
	ds_write2st64_b32 v9, v19, v11 offset0:6 offset1:7
	v_fma_f32 v11, -v17, v18, 1.0
	s_waitcnt lgkmcnt(1)
	v_add_f32_e32 v10, v10, v12
	v_fmac_f32_e32 v18, v11, v18
	ds_bpermute_b32 v11, v15, v10
	v_div_scale_f32 v12, vcc, 1.0, v13, 1.0
	v_mul_f32_e32 v14, v12, v18
	v_fma_f32 v15, -v17, v14, v12
	s_waitcnt lgkmcnt(0)
	v_add_f32_e32 v10, v10, v11
	ds_bpermute_b32 v11, v16, v10
	v_fmac_f32_e32 v14, v15, v18
	v_fma_f32 v12, -v17, v14, v12
	v_div_fmas_f32 v12, v12, v18, v14
	ds_write2st64_b32 v9, v20, v21 offset0:4 offset1:5
	s_waitcnt lgkmcnt(1)
	v_add_f32_e32 v10, v10, v11
	ds_bpermute_b32 v8, v8, v10
	v_div_fixup_f32 v11, v12, v13, 1.0
	v_mul_f32_e32 v0, v0, v11
	v_mul_f32_e32 v1, v1, v11
	ds_write2st64_b32 v9, v0, v1 offset0:8 offset1:9
	s_waitcnt lgkmcnt(1)
	v_add_f32_e32 v0, v10, v8
	v_div_scale_f32 v1, s[0:1], v0, v0, 1.0
	v_rcp_f32_e32 v8, v1
	v_mul_f32_e32 v2, v2, v11
	v_mul_f32_e32 v3, v3, v11
	ds_write2st64_b32 v9, v2, v3 offset0:10 offset1:11
	v_fma_f32 v2, -v1, v8, 1.0
	v_fmac_f32_e32 v8, v2, v8
	v_div_scale_f32 v2, vcc, 1.0, v0, 1.0
	v_mul_f32_e32 v3, v2, v8
	v_fma_f32 v10, -v1, v3, v2
	v_fmac_f32_e32 v3, v10, v8
	v_fma_f32 v1, -v1, v3, v2
	v_div_fmas_f32 v1, v1, v8, v3
	v_div_fixup_f32 v0, v1, v0, 1.0
	v_mul_f32_e32 v1, v4, v0
	v_mul_f32_e32 v2, v5, v0
	ds_write2st64_b32 v9, v1, v2 offset0:12 offset1:13
	v_mul_f32_e32 v1, v6, v0
	v_mul_f32_e32 v0, v7, v0
	s_lshl_b64 s[0:1], s[34:35], 20
	ds_write2st64_b32 v9, v1, v0 offset0:14 offset1:15
	s_add_u32 s0, s42, s0
	v_lshlrev_b32_e32 v0, 1, v117
	s_addc_u32 s1, s43, s1
	v_ashrrev_i32_e32 v1, 31, v0
	v_lshl_add_u64 v[2:3], v[0:1], 2, s[0:1]
	v_add_co_u32_e32 v4, vcc, s51, v2
	s_waitcnt lgkmcnt(0)
	s_nop 0
	v_addc_co_u32_e32 v5, vcc, 0, v3, vcc
	v_add_co_u32_e32 v6, vcc, s21, v2
	s_barrier
	s_nop 0
	v_addc_co_u32_e32 v7, vcc, 0, v3, vcc
	global_load_dwordx2 v[54:55], v[4:5], off offset:-4096 nt
	global_load_dwordx2 v[50:51], v[4:5], off nt
	global_load_dwordx2 v[48:49], v[6:7], off offset:-4096 nt
	global_load_dwordx2 v[46:47], v[6:7], off nt
	v_add_co_u32_e32 v6, vcc, s54, v2
	s_mov_b32 s0, 0
	s_nop 0
	v_addc_co_u32_e32 v7, vcc, 0, v3, vcc
	v_add_co_u32_e32 v12, vcc, s55, v2
	s_nop 1
	v_addc_co_u32_e32 v13, vcc, 0, v3, vcc
	global_load_dwordx2 v[4:5], v[6:7], off offset:-4096 nt
	global_load_dwordx2 v[10:11], v[6:7], off nt
	global_load_dwordx2 v[8:9], v[12:13], off offset:-4096 nt
	s_nop 0
	global_load_dwordx2 v[6:7], v[12:13], off nt
	v_add_co_u32_e32 v12, vcc, s56, v2
	s_nop 1
	v_addc_co_u32_e32 v13, vcc, 0, v3, vcc
	v_add_co_u32_e32 v20, vcc, s57, v2
	s_nop 1
	v_addc_co_u32_e32 v21, vcc, 0, v3, vcc
	global_load_dwordx2 v[18:19], v[12:13], off offset:-4096 nt
	global_load_dwordx2 v[16:17], v[12:13], off nt
	global_load_dwordx2 v[14:15], v[20:21], off offset:-4096 nt
	s_nop 0
	global_load_dwordx2 v[12:13], v[20:21], off nt
	v_add_co_u32_e32 v20, vcc, 0xd000, v2
	s_nop 1
	v_addc_co_u32_e32 v21, vcc, 0, v3, vcc
	v_add_co_u32_e32 v22, vcc, 0xe000, v2
	s_nop 1
	v_addc_co_u32_e32 v23, vcc, 0, v3, vcc
	v_add_co_u32_e32 v26, vcc, 0xf000, v2
	s_nop 1
	v_addc_co_u32_e32 v27, vcc, 0, v3, vcc
	global_load_dwordx2 v[82:83], v[2:3], off nt
	global_load_dwordx2 v[24:25], v[20:21], off nt
	s_nop 0
	global_load_dwordx2 v[22:23], v[22:23], off nt
	s_nop 0
	global_load_dwordx2 v[20:21], v[26:27], off nt
; __device__ __forceinline__ void memattn_unit(const Ctx& C, int r0, const float* kp0, const float* vp0, unsigned char* lds, int lane) {
;     ...
; #pragma unroll 1
;         for (int m0 = 0; m0 < 256; m0 += 16) {
;             float2 vb[16];
;             const int mn = (m0 + 16 < 256) ? m0 + 16 : m0;
; #pragma unroll
;             for (int u = 0; u < 16; ++u) vb[u] = *(const float2*)(vbase + (size_t)(mn + u) * 1024);
; #pragma unroll
;             for (int hf = 0; hf < 2; ++hf) {
; #pragma unroll
;                 for (int qi = 0; qi < 8; ++qi) {
;                     const float* pr = logits + (qi * 4 + hw) * 256 + m0 + 8 * hf;
;                     const f32x4 p0 = *(const f32x4*)pr, p1 = *(const f32x4*)(pr + 4);
;                     acc[qi][0] = fmaf(p0.x, va[8 * hf + 0].x, acc[qi][0]); acc[qi][1] = fmaf(p0.x, va[8 * hf + 0].y, acc[qi][1]);
;                     acc[qi][0] = fmaf(p0.y, va[8 * hf + 1].x, acc[qi][0]); acc[qi][1] = fmaf(p0.y, va[8 * hf + 1].y, acc[qi][1]);
;                     acc[qi][0] = fmaf(p0.z, va[8 * hf + 2].x, acc[qi][0]); acc[qi][1] = fmaf(p0.z, va[8 * hf + 2].y, acc[qi][1]);
;                     acc[qi][0] = fmaf(p0.w, va[8 * hf + 3].x, acc[qi][0]); acc[qi][1] = fmaf(p0.w, va[8 * hf + 3].y, acc[qi][1]);
;                     acc[qi][0] = fmaf(p1.x, va[8 * hf + 4].x, acc[qi][0]); acc[qi][1] = fmaf(p1.x, va[8 * hf + 4].y, acc[qi][1]);
;                     acc[qi][0] = fmaf(p1.y, va[8 * hf + 5].x, acc[qi][0]); acc[qi][1] = fmaf(p1.y, va[8 * hf + 5].y, acc[qi][1]);
;                     acc[qi][0] = fmaf(p1.z, va[8 * hf + 6].x, acc[qi][0]); acc[qi][1] = fmaf(p1.z, va[8 * hf + 6].y, acc[qi][1]);
;                     acc[qi][0] = fmaf(p1.w, va[8 * hf + 7].x, acc[qi][0]); acc[qi][1] = fmaf(p1.w, va[8 * hf + 7].y, acc[qi][1]);
;                 }
.LBB0_3211:
	s_add_i32 s5, s0, 16
	s_cmpk_lt_u32 s0, 0xf0
	s_cselect_b64 s[6:7], -1, 0
	s_and_b64 vcc, s[6:7], exec
	s_cselect_b32 s0, s5, s0
	s_lshl_b32 s12, s0, 10
	v_lshl_add_u64 v[60:61], s[12:13], 2, v[2:3]
	v_add_co_u32_e64 v28, s[0:1], s51, v60
	v_mov_b32_e32 v117, s4
	s_nop 0
	v_addc_co_u32_e64 v29, s[0:1], 0, v61, s[0:1]
	v_add_co_u32_e64 v32, s[0:1], s21, v60
	s_nop 1
	v_addc_co_u32_e64 v33, s[0:1], 0, v61, s[0:1]
	v_add_co_u32_e64 v36, s[0:1], s54, v60
	global_load_dwordx2 v[26:27], v[28:29], off offset:-4096 nt
	s_nop 0
	global_load_dwordx2 v[28:29], v[28:29], off nt
	s_nop 0
	global_load_dwordx2 v[30:31], v[32:33], off offset:-4096 nt
	s_nop 0
	global_load_dwordx2 v[32:33], v[32:33], off nt
	v_addc_co_u32_e64 v37, s[0:1], 0, v61, s[0:1]
	v_add_co_u32_e64 v40, s[0:1], s55, v60
	s_nop 1
	v_addc_co_u32_e64 v41, s[0:1], 0, v61, s[0:1]
	v_add_co_u32_e64 v52, s[0:1], s56, v60
	global_load_dwordx2 v[42:43], v[36:37], off offset:-4096 nt
	s_nop 0
	global_load_dwordx2 v[36:37], v[36:37], off nt
	s_nop 0
	global_load_dwordx2 v[38:39], v[40:41], off offset:-4096 nt
	s_nop 0
	global_load_dwordx2 v[40:41], v[40:41], off nt
	v_addc_co_u32_e64 v53, s[0:1], 0, v61, s[0:1]
	v_add_co_u32_e64 v66, s[0:1], s57, v60
	s_nop 1
	v_addc_co_u32_e64 v67, s[0:1], 0, v61, s[0:1]
	v_add_co_u32_e64 v78, s[0:1], s58, v60
	global_load_dwordx2 v[44:45], v[52:53], off offset:-4096 nt
	s_nop 0
	global_load_dwordx2 v[52:53], v[52:53], off nt
	s_nop 0
	global_load_dwordx2 v[62:63], v[66:67], off offset:-4096 nt
	s_nop 0
	global_load_dwordx2 v[66:67], v[66:67], off nt
	v_addc_co_u32_e64 v79, s[0:1], 0, v61, s[0:1]
	v_add_co_u32_e64 v80, s[0:1], s59, v60
	global_load_dwordx2 v[76:77], v[78:79], off offset:-4096 nt
	s_nop 0
	global_load_dwordx2 v[78:79], v[78:79], off nt
	v_addc_co_u32_e64 v81, s[0:1], 0, v61, s[0:1]
	global_load_dwordx2 v[60:61], v[60:61], off nt
	s_nop 0
	global_load_dwordx2 v[80:81], v[80:81], off nt
	ds_read_b128 v[84:87], v117
	ds_read_b128 v[88:91], v117 offset:16
	ds_read_b128 v[92:95], v117 offset:4096
	ds_read_b128 v[96:99], v117 offset:8192
	ds_read_b128 v[100:103], v117 offset:12288
	s_waitcnt vmcnt(19) lgkmcnt(4)
	v_pk_fma_f32 v[58:59], v[84:85], v[82:83], v[58:59] op_sel_hi:[0,1,1]
	v_pk_fma_f32 v[58:59], v[84:85], v[54:55], v[58:59] op_sel:[1,0,0]
	v_mov_b32_e32 v84, v87
	v_pk_fma_f32 v[58:59], v[86:87], v[50:51], v[58:59] op_sel_hi:[0,1,1]
	v_pk_fma_f32 v[58:59], v[84:85], v[48:49], v[58:59] op_sel_hi:[0,1,1]
	ds_read_b128 v[84:87], v117 offset:4112
	s_waitcnt lgkmcnt(4)
	v_pk_fma_f32 v[112:113], v[88:89], v[46:47], v[58:59] op_sel_hi:[0,1,1]
	s_waitcnt lgkmcnt(3)
	v_pk_fma_f32 v[58:59], v[92:93], v[82:83], v[68:69] op_sel_hi:[0,1,1]
	v_pk_fma_f32 v[58:59], v[92:93], v[54:55], v[58:59] op_sel:[1,0,0]
	v_mov_b32_e32 v68, v95
	v_pk_fma_f32 v[58:59], v[94:95], v[50:51], v[58:59] op_sel_hi:[0,1,1]
	v_pk_fma_f32 v[58:59], v[68:69], v[48:49], v[58:59] op_sel_hi:[0,1,1]
	ds_read_b128 v[92:95], v117 offset:8208
	s_waitcnt lgkmcnt(1)
	v_pk_fma_f32 v[122:123], v[84:85], v[46:47], v[58:59] op_sel_hi:[0,1,1]
	v_pk_fma_f32 v[58:59], v[96:97], v[82:83], v[72:73] op_sel_hi:[0,1,1]
	v_pk_fma_f32 v[58:59], v[96:97], v[54:55], v[58:59] op_sel:[1,0,0]
	v_mov_b32_e32 v68, v99
	v_pk_fma_f32 v[58:59], v[98:99], v[50:51], v[58:59] op_sel_hi:[0,1,1]
	ds_read_b128 v[96:99], v117 offset:12304
	v_pk_fma_f32 v[56:57], v[100:101], v[82:83], v[56:57] op_sel_hi:[0,1,1]
	v_pk_fma_f32 v[58:59], v[68:69], v[48:49], v[58:59] op_sel_hi:[0,1,1]
	v_pk_fma_f32 v[56:57], v[100:101], v[54:55], v[56:57] op_sel:[1,0,0]
	s_waitcnt lgkmcnt(1)
	v_pk_fma_f32 v[72:73], v[92:93], v[46:47], v[58:59] op_sel_hi:[0,1,1]
	v_pk_fma_f32 v[68:69], v[102:103], v[50:51], v[56:57] op_sel_hi:[0,1,1]
	ds_read_b128 v[56:59], v117 offset:16384
	v_mov_b32_e32 v100, v103
	v_pk_fma_f32 v[68:69], v[100:101], v[48:49], v[68:69] op_sel_hi:[0,1,1]
	ds_read_b128 v[100:103], v117 offset:16400
	ds_read_b128 v[104:107], v117 offset:20480
	ds_read_b128 v[108:111], v117 offset:20496
	s_waitcnt lgkmcnt(3)
	v_pk_fma_f32 v[64:65], v[56:57], v[82:83], v[64:65] op_sel_hi:[0,1,1]
	v_pk_fma_f32 v[56:57], v[56:57], v[54:55], v[64:65] op_sel:[1,0,0]
	v_pk_fma_f32 v[124:125], v[96:97], v[46:47], v[68:69] op_sel_hi:[0,1,1]
	v_pk_fma_f32 v[56:57], v[58:59], v[50:51], v[56:57] op_sel_hi:[0,1,1]
	v_mov_b32_e32 v58, v59
	v_pk_fma_f32 v[56:57], v[58:59], v[48:49], v[56:57] op_sel_hi:[0,1,1]
	s_waitcnt lgkmcnt(2)
	v_pk_fma_f32 v[64:65], v[100:101], v[46:47], v[56:57] op_sel_hi:[0,1,1]
	s_waitcnt lgkmcnt(1)
	v_pk_fma_f32 v[56:57], v[104:105], v[82:83], v[70:71] op_sel_hi:[0,1,1]
	v_pk_fma_f32 v[56:57], v[104:105], v[54:55], v[56:57] op_sel:[1,0,0]
	v_mov_b32_e32 v70, v107
	v_pk_fma_f32 v[68:69], v[106:107], v[50:51], v[56:57] op_sel_hi:[0,1,1]
	ds_read_b128 v[56:59], v117 offset:24576
	ds_read_b128 v[104:107], v117 offset:24592
	v_pk_fma_f32 v[68:69], v[70:71], v[48:49], v[68:69] op_sel_hi:[0,1,1]
	s_waitcnt lgkmcnt(2)
	v_pk_fma_f32 v[126:127], v[108:109], v[46:47], v[68:69] op_sel_hi:[0,1,1]
	ds_read_b128 v[118:121], v117 offset:28688
	s_waitcnt lgkmcnt(2)
	v_pk_fma_f32 v[68:69], v[56:57], v[82:83], v[74:75] op_sel_hi:[0,1,1]
	v_pk_fma_f32 v[56:57], v[56:57], v[54:55], v[68:69] op_sel:[1,0,0]
	ds_read_b128 v[68:71], v117 offset:28672
	v_pk_fma_f32 v[56:57], v[58:59], v[50:51], v[56:57] op_sel_hi:[0,1,1]
	v_mov_b32_e32 v58, v59
	v_pk_fma_f32 v[56:57], v[58:59], v[48:49], v[56:57] op_sel_hi:[0,1,1]
	s_waitcnt lgkmcnt(2)
	v_pk_fma_f32 v[74:75], v[104:105], v[46:47], v[56:57] op_sel_hi:[0,1,1]
	s_waitcnt lgkmcnt(0)
; __device__ __forceinline__ void memattn_unit(const Ctx& C, int r0, const float* kp0, const float* vp0, unsigned char* lds, int lane) {
;     ...
;             for (int hf = 0; hf < 2; ++hf) {
; #pragma unroll
;                 for (int qi = 0; qi < 8; ++qi) {
;                     const float* pr = logits + (qi * 4 + hw) * 256 + m0 + 8 * hf;
;                     const f32x4 p0 = *(const f32x4*)pr, p1 = *(const f32x4*)(pr + 4);
;                     acc[qi][0] = fmaf(p0.x, va[8 * hf + 0].x, acc[qi][0]); acc[qi][1] = fmaf(p0.x, va[8 * hf + 0].y, acc[qi][1]);
;                     acc[qi][0] = fmaf(p0.y, va[8 * hf + 1].x, acc[qi][0]); acc[qi][1] = fmaf(p0.y, va[8 * hf + 1].y, acc[qi][1]);
;                     acc[qi][0] = fmaf(p0.z, va[8 * hf + 2].x, acc[qi][0]); acc[qi][1] = fmaf(p0.z, va[8 * hf + 2].y, acc[qi][1]);
;                     acc[qi][0] = fmaf(p0.w, va[8 * hf + 3].x, acc[qi][0]); acc[qi][1] = fmaf(p0.w, va[8 * hf + 3].y, acc[qi][1]);
;                     acc[qi][0] = fmaf(p1.x, va[8 * hf + 4].x, acc[qi][0]); acc[qi][1] = fmaf(p1.x, va[8 * hf + 4].y, acc[qi][1]);
;                     acc[qi][0] = fmaf(p1.y, va[8 * hf + 5].x, acc[qi][0]); acc[qi][1] = fmaf(p1.y, va[8 * hf + 5].y, acc[qi][1]);
;                     acc[qi][0] = fmaf(p1.z, va[8 * hf + 6].x, acc[qi][0]); acc[qi][1] = fmaf(p1.z, va[8 * hf + 6].y, acc[qi][1]);
;                     acc[qi][0] = fmaf(p1.w, va[8 * hf + 7].x, acc[qi][0]); acc[qi][1] = fmaf(p1.w, va[8 * hf + 7].y, acc[qi][1]);
;                 }
	v_pk_fma_f32 v[34:35], v[68:69], v[82:83], v[34:35] op_sel_hi:[0,1,1]
	v_pk_fma_f32 v[34:35], v[68:69], v[54:55], v[34:35] op_sel:[1,0,0]
	s_nop 0
	v_pk_fma_f32 v[34:35], v[70:71], v[50:51], v[34:35] op_sel_hi:[0,1,1]
	v_mov_b32_e32 v50, v71
	v_pk_fma_f32 v[34:35], v[50:51], v[48:49], v[34:35] op_sel_hi:[0,1,1]
	v_pk_fma_f32 v[34:35], v[118:119], v[46:47], v[34:35] op_sel_hi:[0,1,1]
	ds_read_b128 v[46:49], v117 offset:32
	ds_read_b128 v[54:57], v117 offset:48
	v_pk_fma_f32 v[50:51], v[88:89], v[4:5], v[112:113] op_sel:[1,0,0]
	v_mov_b32_e32 v58, v91
	v_pk_fma_f32 v[50:51], v[90:91], v[10:11], v[50:51] op_sel_hi:[0,1,1]
	v_pk_fma_f32 v[50:51], v[58:59], v[8:9], v[50:51] op_sel_hi:[0,1,1]
	s_waitcnt lgkmcnt(1)
	v_pk_fma_f32 v[50:51], v[46:47], v[6:7], v[50:51] op_sel_hi:[0,1,1]
	v_pk_fma_f32 v[46:47], v[46:47], v[18:19], v[50:51] op_sel:[1,0,0]
	v_pk_fma_f32 v[50:51], v[84:85], v[4:5], v[122:123] op_sel:[1,0,0]
	v_pk_fma_f32 v[46:47], v[48:49], v[16:17], v[46:47] op_sel_hi:[0,1,1]
	v_mov_b32_e32 v48, v49
	v_pk_fma_f32 v[46:47], v[48:49], v[14:15], v[46:47] op_sel_hi:[0,1,1]
	s_waitcnt lgkmcnt(0)
	v_pk_fma_f32 v[46:47], v[54:55], v[12:13], v[46:47] op_sel_hi:[0,1,1]
	s_waitcnt vmcnt(18)
	v_pk_fma_f32 v[46:47], v[54:55], v[24:25], v[46:47] op_sel:[1,0,0]
	v_mov_b32_e32 v48, v57
	s_waitcnt vmcnt(17)
	v_pk_fma_f32 v[46:47], v[56:57], v[22:23], v[46:47] op_sel_hi:[0,1,1]
	s_waitcnt vmcnt(16)
	v_pk_fma_f32 v[58:59], v[48:49], v[20:21], v[46:47] op_sel_hi:[0,1,1]
	ds_read_b128 v[46:49], v117 offset:4128
	ds_read_b128 v[54:57], v117 offset:4144
	v_pk_fma_f32 v[50:51], v[86:87], v[10:11], v[50:51] op_sel_hi:[0,1,1]
	v_mov_b32_e32 v68, v87
	v_pk_fma_f32 v[50:51], v[68:69], v[8:9], v[50:51] op_sel_hi:[0,1,1]
	s_waitcnt lgkmcnt(1)
	v_pk_fma_f32 v[50:51], v[46:47], v[6:7], v[50:51] op_sel_hi:[0,1,1]
	v_pk_fma_f32 v[46:47], v[46:47], v[18:19], v[50:51] op_sel:[1,0,0]
	v_pk_fma_f32 v[50:51], v[92:93], v[4:5], v[72:73] op_sel:[1,0,0]
	v_pk_fma_f32 v[46:47], v[48:49], v[16:17], v[46:47] op_sel_hi:[0,1,1]
	v_mov_b32_e32 v48, v49
	v_pk_fma_f32 v[46:47], v[48:49], v[14:15], v[46:47] op_sel_hi:[0,1,1]
	s_waitcnt lgkmcnt(0)
	v_pk_fma_f32 v[46:47], v[54:55], v[12:13], v[46:47] op_sel_hi:[0,1,1]
	v_pk_fma_f32 v[46:47], v[54:55], v[24:25], v[46:47] op_sel:[1,0,0]
	v_mov_b32_e32 v48, v57
	v_pk_fma_f32 v[46:47], v[56:57], v[22:23], v[46:47] op_sel_hi:[0,1,1]
	v_pk_fma_f32 v[68:69], v[48:49], v[20:21], v[46:47] op_sel_hi:[0,1,1]
	ds_read_b128 v[46:49], v117 offset:8224
	ds_read_b128 v[54:57], v117 offset:8240
	v_pk_fma_f32 v[50:51], v[94:95], v[10:11], v[50:51] op_sel_hi:[0,1,1]
	v_mov_b32_e32 v70, v95
	v_pk_fma_f32 v[50:51], v[70:71], v[8:9], v[50:51] op_sel_hi:[0,1,1]
	s_waitcnt lgkmcnt(1)
	v_pk_fma_f32 v[50:51], v[46:47], v[6:7], v[50:51] op_sel_hi:[0,1,1]
	v_pk_fma_f32 v[46:47], v[46:47], v[18:19], v[50:51] op_sel:[1,0,0]
	v_pk_fma_f32 v[50:51], v[96:97], v[4:5], v[124:125] op_sel:[1,0,0]
	v_pk_fma_f32 v[46:47], v[48:49], v[16:17], v[46:47] op_sel_hi:[0,1,1]
	v_mov_b32_e32 v48, v49
	v_pk_fma_f32 v[46:47], v[48:49], v[14:15], v[46:47] op_sel_hi:[0,1,1]
	s_waitcnt lgkmcnt(0)
	v_pk_fma_f32 v[46:47], v[54:55], v[12:13], v[46:47] op_sel_hi:[0,1,1]
	v_pk_fma_f32 v[46:47], v[54:55], v[24:25], v[46:47] op_sel:[1,0,0]
	v_mov_b32_e32 v48, v57
	v_pk_fma_f32 v[46:47], v[56:57], v[22:23], v[46:47] op_sel_hi:[0,1,1]
	v_pk_fma_f32 v[72:73], v[48:49], v[20:21], v[46:47] op_sel_hi:[0,1,1]
	ds_read_b128 v[46:49], v117 offset:12320
	ds_read_b128 v[54:57], v117 offset:12336
	v_pk_fma_f32 v[50:51], v[98:99], v[10:11], v[50:51] op_sel_hi:[0,1,1]
	v_mov_b32_e32 v70, v99
	v_pk_fma_f32 v[50:51], v[70:71], v[8:9], v[50:51] op_sel_hi:[0,1,1]
	s_waitcnt lgkmcnt(1)
	v_pk_fma_f32 v[50:51], v[46:47], v[6:7], v[50:51] op_sel_hi:[0,1,1]
	v_pk_fma_f32 v[46:47], v[46:47], v[18:19], v[50:51] op_sel:[1,0,0]
	v_pk_fma_f32 v[50:51], v[100:101], v[4:5], v[64:65] op_sel:[1,0,0]
	v_pk_fma_f32 v[46:47], v[48:49], v[16:17], v[46:47] op_sel_hi:[0,1,1]
	v_mov_b32_e32 v48, v49
	v_pk_fma_f32 v[46:47], v[48:49], v[14:15], v[46:47] op_sel_hi:[0,1,1]
	s_waitcnt lgkmcnt(0)
	v_pk_fma_f32 v[46:47], v[54:55], v[12:13], v[46:47] op_sel_hi:[0,1,1]
	v_pk_fma_f32 v[46:47], v[54:55], v[24:25], v[46:47] op_sel:[1,0,0]
	v_mov_b32_e32 v48, v57
	v_pk_fma_f32 v[46:47], v[56:57], v[22:23], v[46:47] op_sel_hi:[0,1,1]
	v_pk_fma_f32 v[56:57], v[48:49], v[20:21], v[46:47] op_sel_hi:[0,1,1]
	ds_read_b128 v[46:49], v117 offset:16416
	ds_read_b128 v[82:85], v117 offset:16432
	v_pk_fma_f32 v[50:51], v[102:103], v[10:11], v[50:51] op_sel_hi:[0,1,1]
	v_mov_b32_e32 v54, v103
	v_pk_fma_f32 v[50:51], v[54:55], v[8:9], v[50:51] op_sel_hi:[0,1,1]
	s_waitcnt lgkmcnt(1)
	v_pk_fma_f32 v[50:51], v[46:47], v[6:7], v[50:51] op_sel_hi:[0,1,1]
	v_pk_fma_f32 v[46:47], v[46:47], v[18:19], v[50:51] op_sel:[1,0,0]
	v_pk_fma_f32 v[50:51], v[108:109], v[4:5], v[126:127] op_sel:[1,0,0]
	v_pk_fma_f32 v[46:47], v[48:49], v[16:17], v[46:47] op_sel_hi:[0,1,1]
	v_mov_b32_e32 v48, v49
	v_pk_fma_f32 v[46:47], v[48:49], v[14:15], v[46:47] op_sel_hi:[0,1,1]
	s_waitcnt lgkmcnt(0)
; __device__ __forceinline__ unsigned cvt_pk_bf16(float lo, float hi) { unsigned r; asm volatile("v_cvt_pk_bf16_f32 %0, %1, %2" : "=v"(r) : "v"(lo), "v"(hi)); return r; }
; __device__ __forceinline__ void memattn_unit(const Ctx& C, int r0, const float* kp0, const float* vp0, unsigned char* lds, int lane) {
;     ...
;             for (int hf = 0; hf < 2; ++hf) {
; #pragma unroll
;                 for (int qi = 0; qi < 8; ++qi) {
;                     const float* pr = logits + (qi * 4 + hw) * 256 + m0 + 8 * hf;
;                     const f32x4 p0 = *(const f32x4*)pr, p1 = *(const f32x4*)(pr + 4);
;                     acc[qi][0] = fmaf(p0.x, va[8 * hf + 0].x, acc[qi][0]); acc[qi][1] = fmaf(p0.x, va[8 * hf + 0].y, acc[qi][1]);
;                     acc[qi][0] = fmaf(p0.y, va[8 * hf + 1].x, acc[qi][0]); acc[qi][1] = fmaf(p0.y, va[8 * hf + 1].y, acc[qi][1]);
;                     acc[qi][0] = fmaf(p0.z, va[8 * hf + 2].x, acc[qi][0]); acc[qi][1] = fmaf(p0.z, va[8 * hf + 2].y, acc[qi][1]);
;                     acc[qi][0] = fmaf(p0.w, va[8 * hf + 3].x, acc[qi][0]); acc[qi][1] = fmaf(p0.w, va[8 * hf + 3].y, acc[qi][1]);
;                     acc[qi][0] = fmaf(p1.x, va[8 * hf + 4].x, acc[qi][0]); acc[qi][1] = fmaf(p1.x, va[8 * hf + 4].y, acc[qi][1]);
;                     acc[qi][0] = fmaf(p1.y, va[8 * hf + 5].x, acc[qi][0]); acc[qi][1] = fmaf(p1.y, va[8 * hf + 5].y, acc[qi][1]);
;                     acc[qi][0] = fmaf(p1.z, va[8 * hf + 6].x, acc[qi][0]); acc[qi][1] = fmaf(p1.z, va[8 * hf + 6].y, acc[qi][1]);
;                     acc[qi][0] = fmaf(p1.w, va[8 * hf + 7].x, acc[qi][0]); acc[qi][1] = fmaf(p1.w, va[8 * hf + 7].y, acc[qi][1]);
;                 }
;                 __builtin_amdgcn_sched_barrier(0);
;             }
; #pragma unroll
;             for (int u = 0; u < 16; ++u) va[u] = vb[u];
;         }
;         bf16_t* op = (bf16_t*)(C.ws + WS_OMEM) + (size_t)r0 * 1024 + 128 * w + 2 * lane;
; #pragma unroll
;         for (int qi = 0; qi < 8; ++qi) *(unsigned*)(op + (size_t)qi * 1024) = cvt_pk_bf16(acc[qi][0], acc[qi][1]);
;     }
;     __syncthreads();
	v_pk_fma_f32 v[46:47], v[82:83], v[12:13], v[46:47] op_sel_hi:[0,1,1]
	v_pk_fma_f32 v[46:47], v[82:83], v[24:25], v[46:47] op_sel:[1,0,0]
	v_mov_b32_e32 v48, v85
	v_pk_fma_f32 v[46:47], v[84:85], v[22:23], v[46:47] op_sel_hi:[0,1,1]
	v_pk_fma_f32 v[64:65], v[48:49], v[20:21], v[46:47] op_sel_hi:[0,1,1]
	ds_read_b128 v[46:49], v117 offset:20512
	ds_read_b128 v[82:85], v117 offset:20528
	v_pk_fma_f32 v[50:51], v[110:111], v[10:11], v[50:51] op_sel_hi:[0,1,1]
	v_mov_b32_e32 v54, v111
	v_pk_fma_f32 v[50:51], v[54:55], v[8:9], v[50:51] op_sel_hi:[0,1,1]
	s_waitcnt lgkmcnt(1)
	v_pk_fma_f32 v[50:51], v[46:47], v[6:7], v[50:51] op_sel_hi:[0,1,1]
	v_pk_fma_f32 v[46:47], v[46:47], v[18:19], v[50:51] op_sel:[1,0,0]
	v_pk_fma_f32 v[50:51], v[104:105], v[4:5], v[74:75] op_sel:[1,0,0]
	v_pk_fma_f32 v[46:47], v[48:49], v[16:17], v[46:47] op_sel_hi:[0,1,1]
	v_mov_b32_e32 v48, v49
	v_pk_fma_f32 v[46:47], v[48:49], v[14:15], v[46:47] op_sel_hi:[0,1,1]
	s_waitcnt lgkmcnt(0)
	v_pk_fma_f32 v[46:47], v[82:83], v[12:13], v[46:47] op_sel_hi:[0,1,1]
	v_pk_fma_f32 v[46:47], v[82:83], v[24:25], v[46:47] op_sel:[1,0,0]
	v_mov_b32_e32 v48, v85
	v_pk_fma_f32 v[46:47], v[84:85], v[22:23], v[46:47] op_sel_hi:[0,1,1]
	v_pk_fma_f32 v[70:71], v[48:49], v[20:21], v[46:47] op_sel_hi:[0,1,1]
	ds_read_b128 v[46:49], v117 offset:24608
	ds_read_b128 v[82:85], v117 offset:24624
	v_pk_fma_f32 v[50:51], v[106:107], v[10:11], v[50:51] op_sel_hi:[0,1,1]
	v_mov_b32_e32 v54, v107
	v_pk_fma_f32 v[50:51], v[54:55], v[8:9], v[50:51] op_sel_hi:[0,1,1]
	s_waitcnt lgkmcnt(1)
	v_pk_fma_f32 v[50:51], v[46:47], v[6:7], v[50:51] op_sel_hi:[0,1,1]
	v_pk_fma_f32 v[46:47], v[46:47], v[18:19], v[50:51] op_sel:[1,0,0]
	v_pk_fma_f32 v[4:5], v[118:119], v[4:5], v[34:35] op_sel:[1,0,0]
	v_pk_fma_f32 v[46:47], v[48:49], v[16:17], v[46:47] op_sel_hi:[0,1,1]
	v_mov_b32_e32 v48, v49
	v_pk_fma_f32 v[46:47], v[48:49], v[14:15], v[46:47] op_sel_hi:[0,1,1]
	s_waitcnt lgkmcnt(0)
	v_pk_fma_f32 v[46:47], v[82:83], v[12:13], v[46:47] op_sel_hi:[0,1,1]
	v_pk_fma_f32 v[46:47], v[82:83], v[24:25], v[46:47] op_sel:[1,0,0]
	v_mov_b32_e32 v48, v85
	v_pk_fma_f32 v[46:47], v[84:85], v[22:23], v[46:47] op_sel_hi:[0,1,1]
	v_pk_fma_f32 v[74:75], v[48:49], v[20:21], v[46:47] op_sel_hi:[0,1,1]
	ds_read_b128 v[46:49], v117 offset:28704
	ds_read_b128 v[82:85], v117 offset:28720
	v_pk_fma_f32 v[4:5], v[120:121], v[10:11], v[4:5] op_sel_hi:[0,1,1]
	v_mov_b32_e32 v10, v121
	v_pk_fma_f32 v[4:5], v[10:11], v[8:9], v[4:5] op_sel_hi:[0,1,1]
	s_waitcnt lgkmcnt(1)
	v_pk_fma_f32 v[4:5], v[46:47], v[6:7], v[4:5] op_sel_hi:[0,1,1]
	v_pk_fma_f32 v[4:5], v[46:47], v[18:19], v[4:5] op_sel:[1,0,0]
	v_mov_b32_e32 v6, v49
	v_pk_fma_f32 v[4:5], v[48:49], v[16:17], v[4:5] op_sel_hi:[0,1,1]
	v_pk_fma_f32 v[4:5], v[6:7], v[14:15], v[4:5] op_sel_hi:[0,1,1]
	s_waitcnt lgkmcnt(0)
	v_pk_fma_f32 v[4:5], v[82:83], v[12:13], v[4:5] op_sel_hi:[0,1,1]
	v_pk_fma_f32 v[4:5], v[82:83], v[24:25], v[4:5] op_sel:[1,0,0]
	v_mov_b32_e32 v6, v85
	v_pk_fma_f32 v[4:5], v[84:85], v[22:23], v[4:5] op_sel_hi:[0,1,1]
	v_pk_fma_f32 v[34:35], v[6:7], v[20:21], v[4:5] op_sel_hi:[0,1,1]
	s_add_i32 s4, s4, 64
	s_waitcnt vmcnt(11)
	v_mov_b32_e32 v5, v43
	v_mov_b32_e32 v4, v42
	s_mov_b32 s0, s5
	s_waitcnt vmcnt(0)
	v_mov_b64_e32 v[20:21], v[80:81]
	v_mov_b64_e32 v[22:23], v[78:79]
	v_mov_b64_e32 v[24:25], v[76:77]
	v_mov_b64_e32 v[12:13], v[66:67]
	v_mov_b64_e32 v[14:15], v[62:63]
	v_mov_b64_e32 v[16:17], v[52:53]
	v_mov_b64_e32 v[18:19], v[44:45]
	v_mov_b64_e32 v[6:7], v[40:41]
	v_mov_b64_e32 v[8:9], v[38:39]
	v_mov_b64_e32 v[10:11], v[36:37]
	v_mov_b64_e32 v[46:47], v[32:33]
	v_mov_b64_e32 v[48:49], v[30:31]
	v_mov_b64_e32 v[50:51], v[28:29]
	v_mov_b64_e32 v[54:55], v[26:27]
	v_mov_b64_e32 v[82:83], v[60:61]
	s_cbranch_vccnz .LBB0_3211
	s_add_u32 s0, s45, s36
	s_addc_u32 s1, s46, s37
	v_lshl_add_u64 v[0:1], v[0:1], 1, s[0:1]
	v_cvt_pk_bf16_f32 v2, v58, v59
	global_store_dword v[0:1], v2, off
	v_cvt_pk_bf16_f32 v2, v68, v69
	global_store_dword v[0:1], v2, off offset:2048
	v_add_co_u32_e32 v2, vcc, s50, v0
	v_cvt_pk_bf16_f32 v6, v72, v73
	s_add_i32 s34, s34, s20
	s_nop 0
	v_addc_co_u32_e32 v3, vcc, 0, v1, vcc
	v_add_co_u32_e32 v4, vcc, s51, v0
	s_add_u32 s22, s22, s24
	s_nop 0
	v_addc_co_u32_e32 v5, vcc, 0, v1, vcc
	global_store_dword v[4:5], v6, off offset:-4096
	v_cvt_pk_bf16_f32 v6, v56, v57
	global_store_dword v[2:3], v6, off offset:2048
	v_cvt_pk_bf16_f32 v2, v64, v65
	global_store_dword v[4:5], v2, off
	v_cvt_pk_bf16_f32 v2, v70, v71
	v_add_co_u32_e32 v0, vcc, s52, v0
	s_addc_u32 s23, s23, s25
	global_store_dword v[4:5], v2, off offset:2048
	v_cvt_pk_bf16_f32 v2, v74, v75
	v_addc_co_u32_e32 v1, vcc, 0, v1, vcc
	s_cmpk_lt_i32 s34, 0x80
	global_store_dword v[0:1], v2, off
	v_cvt_pk_bf16_f32 v2, v34, v35
	global_store_dword v[0:1], v2, off offset:2048
	s_barrier
	s_cbranch_scc1 .LBB0_3144
